# combo27: combo26 + fix_rows (conv seam rows before the down projection): the second batch of four parameter loads of each column-block iteration is issued with the first batch (one memory round trip p
# speedup vs baseline: 1.0067x; 1.0015x over previous
; __device__ __forceinline__ unsigned pk2(float lo, float hi) { f32x2_t v = {lo, hi}; bf16x2_t b = __builtin_convertvector(v, bf16x2_t); return __builtin_bit_cast(unsigned, b); }
; __device__ __forceinline__ float sigmoidf_(float v) { return fast_rcp(1.0f + fast_exp2(-v * LOG2E)); }
; __device__ __forceinline__ void fix_rows(bf16_t* A, const float* edge, const float* cw, const float* cb, int pm, int tid) {
;     ...
;         for (int gv = 0; gv < 2; ++gv) {
;             const int col = gv * 128 + ci, cc = gv * DFF + ch;
;             const float u0 = E[col], u1 = E[256 + col], p254 = hasprev ? P[512 + col] : 0.f, p255 = hasprev ? P[768 + col] : 0.f;
;             const float w0 = cw[cc], w1 = cw[UPN + cc], w2 = cw[2 * UPN + cc], bb = cb[cc];
;             c0[gv] = bb + w0 * p254 + w1 * p255 + w2 * u0; c1[gv] = bb + w0 * p255 + w1 * u0 + w2 * u1;
;         }
;         const float a0 = c0[0] * sigmoidf_(c0[0]) * c0[1], a1 = c1[0] * sigmoidf_(c1[0]) * c1[1];
;         A[(size_t)(pm * 256) * DFF + ch] = (bf16_t)(pk2(a0, 0.f) & 0xffffu);
;         A[(size_t)(pm * 256 + 1) * DFF + ch] = (bf16_t)(pk2(a1, 0.f) & 0xffffu);
.LBB0_784:
	v_add_co_u32_e32 v18, vcc, 0x5000, v10
	s_nop 0
	s_nop 0
	v_addc_co_u32_e32 v19, vcc, 0, v11, vcc
	v_add_co_u32_e32 v38, vcc, 0xa000, v10
	s_nop 0
	s_nop 0
	v_addc_co_u32_e32 v39, vcc, 0, v11, vcc
	v_add_co_u32_e32 v10, vcc, 0x10000, v10
	s_mov_b64 s[22:23], vcc
	v_add_co_u32_e32 v12, vcc, 0x5000, v12
	s_nop 0
	s_nop 0
	v_addc_co_u32_e32 v13, vcc, 0, v13, vcc
	global_load_dword v40, v[12:13], off offset:1024
	s_nop 0
	global_load_dword v18, v[18:19], off offset:1024
	s_nop 0
	global_load_dword v19, v[38:39], off offset:3072
	v_addc_co_u32_e64 v11, vcc, 0, v11, s[22:23]
	global_load_dword v38, v[10:11], off offset:1024
	s_waitcnt vmcnt(6)
	v_fma_f32 v33, v33, v36, v31
	v_fmac_f32_e32 v33, v32, v35
	v_fmac_f32_e32 v33, v28, v37
	v_fmac_f32_e32 v31, v32, v36
	v_mul_f32_e32 v10, 0xbfb8aa3b, v33
	v_fmac_f32_e32 v31, v28, v35
	v_exp_f32_e32 v13, v10
	v_fmac_f32_e32 v31, v29, v37
	v_mul_f32_e32 v11, 0xbfb8aa3b, v31
	v_exp_f32_e32 v28, v11
	v_add_f32_e32 v13, 1.0, v13
	v_add_co_u32_e32 v10, vcc, 0x1000, v16
	v_rcp_f32_e32 v16, v13
	s_nop 0
	v_addc_co_u32_e32 v11, vcc, 0, v17, vcc
	v_add_co_u32_e32 v12, vcc, 0x1000, v14
	v_add_f32_e32 v14, 1.0, v28
	v_rcp_f32_e32 v14, v14
	v_addc_co_u32_e32 v13, vcc, 0, v15, vcc
	v_mul_f32_e32 v15, v33, v16
	v_mul_f32_e32 v14, v31, v14
	s_waitcnt vmcnt(2)
	v_fma_f32 v16, v34, v18, v40
	v_fmac_f32_e32 v40, v21, v18
	s_waitcnt vmcnt(1)
	v_fmac_f32_e32 v16, v21, v19
	v_fmac_f32_e32 v40, v30, v19
	s_waitcnt vmcnt(0)
	v_fmac_f32_e32 v16, v30, v38
	v_fmac_f32_e32 v40, v20, v38
	v_mul_f32_e32 v15, v15, v16
	v_mul_f32_e32 v14, v14, v40
	v_cvt_pk_bf16_f32 v15, v15, s0
	v_cvt_pk_bf16_f32 v14, v14, s0
	global_store_short v[10:11], v15, off offset:1024
	global_store_short v[12:13], v14, off offset:1024

; __device__ __forceinline__ unsigned pk2(float lo, float hi) { f32x2_t v = {lo, hi}; bf16x2_t b = __builtin_convertvector(v, bf16x2_t); return __builtin_bit_cast(unsigned, b); }
; __device__ __forceinline__ float sigmoidf_(float v) { return fast_rcp(1.0f + fast_exp2(-v * LOG2E)); }
; __device__ __forceinline__ void fix_rows(bf16_t* A, const float* edge, const float* cw, const float* cb, int pm, int tid) {
;     ...
;     for (int it_ = 0; it_ < 6; ++it_) {
;         const int ch = tid + 512 * it_; if (ch >= DFF) break;
;         const int pn = ch >> 7, ci = ch & 127;
;         const float* E = edge + (size_t)(pm * 22 + pn) * 1024;
;         const float* P = hasprev ? edge + (size_t)((pm - 1) * 22 + pn) * 1024 : E;
;         float c0[2], c1[2];
; #pragma unroll
;         for (int gv = 0; gv < 2; ++gv) {
;             const int col = gv * 128 + ci, cc = gv * DFF + ch;
;             const float u0 = E[col], u1 = E[256 + col], p254 = hasprev ? P[512 + col] : 0.f, p255 = hasprev ? P[768 + col] : 0.f;
;             const float w0 = cw[cc], w1 = cw[UPN + cc], w2 = cw[2 * UPN + cc], bb = cb[cc];
;             c0[gv] = bb + w0 * p254 + w1 * p255 + w2 * u0; c1[gv] = bb + w0 * p255 + w1 * u0 + w2 * u1;
;         }
;         const float a0 = c0[0] * sigmoidf_(c0[0]) * c0[1], a1 = c1[0] * sigmoidf_(c1[0]) * c1[1];
;         A[(size_t)(pm * 256) * DFF + ch] = (bf16_t)(pk2(a0, 0.f) & 0xffffu);
;         A[(size_t)(pm * 256 + 1) * DFF + ch] = (bf16_t)(pk2(a1, 0.f) & 0xffffu);
.LBB0_803:
	v_add_co_u32_e32 v14, vcc, s2, v10
	s_nop 0
	s_nop 0
	v_addc_co_u32_e32 v15, vcc, 0, v11, vcc
	v_add_co_u32_e32 v16, vcc, s3, v10
	s_nop 0
	s_nop 0
	v_addc_co_u32_e32 v17, vcc, 0, v11, vcc
	global_load_dword v36, v[14:15], off offset:3072
	global_load_dword v37, v[16:17], off offset:1024
	v_add_co_u32_e32 v14, vcc, s2, v12
	s_nop 0
	s_nop 0
	v_addc_co_u32_e32 v15, vcc, 0, v13, vcc
	global_load_dword v38, v[14:15], off offset:3072
	v_add_co_u32_e32 v14, vcc, s33, v10
	s_nop 0
	s_nop 0
	v_addc_co_u32_e32 v15, vcc, 0, v11, vcc
	global_load_dword v39, v[14:15], off offset:3072
	s_waitcnt vmcnt(6)
	v_fma_f32 v32, v32, v33, v28
	v_fmac_f32_e32 v28, v31, v33
	v_fmac_f32_e32 v28, v18, v34
	v_fmac_f32_e32 v28, v19, v35
	v_fmac_f32_e32 v32, v31, v34
	v_mul_f32_e32 v15, 0xbfb8aa3b, v28
	v_fmac_f32_e32 v32, v18, v35
	v_exp_f32_e32 v15, v15
	s_load_dwordx2 s[0:1], s[0:1], 0x98
	v_mul_f32_e32 v14, 0xbfb8aa3b, v32
	v_exp_f32_e32 v14, v14
	v_add_f32_e32 v15, 1.0, v15
	v_rcp_f32_e32 v19, v15
	s_waitcnt lgkmcnt(0)
	s_add_u32 s25, s0, 0x9804000
	v_add_f32_e32 v14, 1.0, v14
	s_mul_i32 s24, s36, 0x160000
	s_addc_u32 s30, s1, 0
	s_lshl_b32 s31, s36, 8
	v_rcp_f32_e32 v18, v14
	s_mul_hi_i32 s1, s31, 0x1600
	s_add_u32 s0, s25, s24
	s_addc_u32 s1, s30, s1
	s_or_b32 s24, s31, 1
	v_mul_f32_e32 v19, v28, v19
	s_mul_hi_i32 s31, s24, 0x1600
	s_mulk_i32 s24, 0x1600
	v_lshl_add_u64 v[16:17], s[0:1], 0, v[8:9]
	s_add_u32 s0, s25, s24
	v_mul_f32_e32 v18, v32, v18
	s_addc_u32 s1, s30, s31
	v_lshl_add_u64 v[14:15], s[0:1], 0, v[8:9]
	s_waitcnt vmcnt(1)
	v_fma_f32 v28, v30, v36, v38
	v_fmac_f32_e32 v38, v29, v36
	v_fmac_f32_e32 v28, v29, v37
	v_fmac_f32_e32 v38, v20, v37
	s_waitcnt vmcnt(0)
	v_fmac_f32_e32 v28, v20, v39
	v_fmac_f32_e32 v38, v21, v39
	v_mul_f32_e32 v18, v18, v28
	v_mul_f32_e32 v19, v19, v38
	v_cvt_pk_bf16_f32 v18, v18, s0
	v_cvt_pk_bf16_f32 v19, v19, s0
	global_store_short v[16:17], v18, off
	global_store_short v[14:15], v19, off
	s_and_b64 exec, exec, s[12:13]
	s_cbranch_execz .LBB0_785
	v_add_u32_e32 v18, s37, v23
	v_ashrrev_i32_e32 v19, 31, v18
	v_lshlrev_b64 v[18:19], 12, v[18:19]
	v_lshl_add_u64 v[18:19], s[28:29], 0, v[18:19]
	v_lshl_add_u64 v[20:21], v[18:19], 0, v[0:1]
	global_load_dword v28, v[20:21], off
	global_load_dword v29, v[20:21], off offset:1024
	v_add_u32_e32 v18, s38, v23
	v_ashrrev_i32_e32 v19, 31, v18
	v_lshlrev_b64 v[18:19], 12, v[18:19]
	v_lshl_add_u64 v[18:19], s[28:29], 0, v[18:19]
	v_mov_b32_e32 v30, 0
	s_and_b64 vcc, exec, s[22:23]
	v_mov_b32_e32 v32, 0
	s_cbranch_vccnz .LBB0_806
	v_lshl_add_u64 v[32:33], v[18:19], 0, v[0:1]
	global_load_dword v32, v[32:33], off offset:2048

; __device__ __forceinline__ unsigned pk2(float lo, float hi) { f32x2_t v = {lo, hi}; bf16x2_t b = __builtin_convertvector(v, bf16x2_t); return __builtin_bit_cast(unsigned, b); }
; __device__ __forceinline__ float sigmoidf_(float v) { return fast_rcp(1.0f + fast_exp2(-v * LOG2E)); }
; __device__ __forceinline__ void fix_rows(bf16_t* A, const float* edge, const float* cw, const float* cb, int pm, int tid) {
;     ...
;     for (int it_ = 0; it_ < 6; ++it_) {
;         const int ch = tid + 512 * it_; if (ch >= DFF) break;
;         const int pn = ch >> 7, ci = ch & 127;
;         const float* E = edge + (size_t)(pm * 22 + pn) * 1024;
;         const float* P = hasprev ? edge + (size_t)((pm - 1) * 22 + pn) * 1024 : E;
;         float c0[2], c1[2];
; #pragma unroll
;         for (int gv = 0; gv < 2; ++gv) {
;             const int col = gv * 128 + ci, cc = gv * DFF + ch;
;             const float u0 = E[col], u1 = E[256 + col], p254 = hasprev ? P[512 + col] : 0.f, p255 = hasprev ? P[768 + col] : 0.f;
;             const float w0 = cw[cc], w1 = cw[UPN + cc], w2 = cw[2 * UPN + cc], bb = cb[cc];
;             c0[gv] = bb + w0 * p254 + w1 * p255 + w2 * u0; c1[gv] = bb + w0 * p255 + w1 * u0 + w2 * u1;
;         }
;         const float a0 = c0[0] * sigmoidf_(c0[0]) * c0[1], a1 = c1[0] * sigmoidf_(c1[0]) * c1[1];
;         A[(size_t)(pm * 256) * DFF + ch] = (bf16_t)(pk2(a0, 0.f) & 0xffffu);
;         A[(size_t)(pm * 256 + 1) * DFF + ch] = (bf16_t)(pk2(a1, 0.f) & 0xffffu);
.LBB0_812:
	v_add_co_u32_e32 v18, vcc, 0x3000, v10
	s_nop 0
	s_nop 0
	v_addc_co_u32_e32 v19, vcc, 0, v11, vcc
	v_add_co_u32_e32 v38, vcc, 0x8000, v10
	s_nop 0
	s_nop 0
	v_addc_co_u32_e32 v39, vcc, 0, v11, vcc
	v_add_co_u32_e32 v40, vcc, 0xe000, v10
	s_mov_b64 s[24:25], vcc
	v_add_co_u32_e32 v42, vcc, 0x3000, v12
	s_nop 0
	s_nop 0
	v_addc_co_u32_e32 v43, vcc, 0, v13, vcc
	global_load_dword v42, v[42:43], off offset:1024
	s_nop 0
	global_load_dword v18, v[18:19], off offset:1024
	s_nop 0
	global_load_dword v19, v[38:39], off offset:3072
	v_addc_co_u32_e64 v41, vcc, 0, v11, s[24:25]
	global_load_dword v38, v[40:41], off offset:1024
	s_waitcnt vmcnt(6)
	v_fma_f32 v32, v32, v35, v33
	v_fmac_f32_e32 v33, v30, v35
	v_fmac_f32_e32 v32, v30, v36
	v_fmac_f32_e32 v33, v28, v36
	v_fmac_f32_e32 v32, v28, v37
	v_fmac_f32_e32 v33, v29, v37
	v_mul_f32_e32 v28, 0xbfb8aa3b, v32
	v_mul_f32_e32 v29, 0xbfb8aa3b, v33
	v_exp_f32_e32 v28, v28
	v_exp_f32_e32 v29, v29
	v_add_f32_e32 v28, 1.0, v28
	v_add_f32_e32 v29, 1.0, v29
	v_rcp_f32_e32 v28, v28
	v_rcp_f32_e32 v29, v29
	v_mul_f32_e32 v28, v32, v28
	v_mul_f32_e32 v29, v33, v29
	s_waitcnt vmcnt(2)
	v_fma_f32 v30, v34, v18, v42
	v_fmac_f32_e32 v42, v21, v18
	s_waitcnt vmcnt(1)
	v_fmac_f32_e32 v30, v21, v19
	v_fmac_f32_e32 v42, v31, v19
	s_waitcnt vmcnt(0)
	v_fmac_f32_e32 v30, v31, v38
	v_fmac_f32_e32 v42, v20, v38
	v_mul_f32_e32 v18, v28, v30
	v_mul_f32_e32 v19, v29, v42
	v_cvt_pk_bf16_f32 v18, v18, s0
	v_cvt_pk_bf16_f32 v19, v19, s0
	global_store_short v[16:17], v18, off offset:1024
	global_store_short v[14:15], v19, off offset:1024
	s_and_b64 exec, exec, s[14:15]
	s_cbranch_execz .LBB0_785
	v_add_u32_e32 v18, s37, v24
	v_ashrrev_i32_e32 v19, 31, v18
	v_lshlrev_b64 v[18:19], 12, v[18:19]
	v_lshl_add_u64 v[18:19], s[28:29], 0, v[18:19]
	v_lshl_add_u64 v[20:21], v[18:19], 0, v[0:1]
	global_load_dword v28, v[20:21], off
	global_load_dword v29, v[20:21], off offset:1024
	v_add_u32_e32 v18, s38, v24
	v_ashrrev_i32_e32 v19, 31, v18
	v_lshlrev_b64 v[18:19], 12, v[18:19]
	v_lshl_add_u64 v[18:19], s[28:29], 0, v[18:19]
	v_mov_b32_e32 v30, 0
	s_and_b64 vcc, exec, s[22:23]
	v_mov_b32_e32 v31, 0
	s_cbranch_vccnz .LBB0_815
	v_lshl_add_u64 v[32:33], v[18:19], 0, v[0:1]
	global_load_dword v31, v[32:33], off offset:2048

; __device__ __forceinline__ unsigned pk2(float lo, float hi) { f32x2_t v = {lo, hi}; bf16x2_t b = __builtin_convertvector(v, bf16x2_t); return __builtin_bit_cast(unsigned, b); }
; __device__ __forceinline__ float sigmoidf_(float v) { return fast_rcp(1.0f + fast_exp2(-v * LOG2E)); }
; __device__ __forceinline__ void fix_rows(bf16_t* A, const float* edge, const float* cw, const float* cb, int pm, int tid) {
;     ...
;     for (int it_ = 0; it_ < 6; ++it_) {
;         const int ch = tid + 512 * it_; if (ch >= DFF) break;
;         const int pn = ch >> 7, ci = ch & 127;
;         const float* E = edge + (size_t)(pm * 22 + pn) * 1024;
;         const float* P = hasprev ? edge + (size_t)((pm - 1) * 22 + pn) * 1024 : E;
;         float c0[2], c1[2];
; #pragma unroll
;         for (int gv = 0; gv < 2; ++gv) {
;             const int col = gv * 128 + ci, cc = gv * DFF + ch;
;             const float u0 = E[col], u1 = E[256 + col], p254 = hasprev ? P[512 + col] : 0.f, p255 = hasprev ? P[768 + col] : 0.f;
;             const float w0 = cw[cc], w1 = cw[UPN + cc], w2 = cw[2 * UPN + cc], bb = cb[cc];
;             c0[gv] = bb + w0 * p254 + w1 * p255 + w2 * u0; c1[gv] = bb + w0 * p255 + w1 * u0 + w2 * u1;
;         }
;         const float a0 = c0[0] * sigmoidf_(c0[0]) * c0[1], a1 = c1[0] * sigmoidf_(c1[0]) * c1[1];
;         A[(size_t)(pm * 256) * DFF + ch] = (bf16_t)(pk2(a0, 0.f) & 0xffffu);
;         A[(size_t)(pm * 256 + 1) * DFF + ch] = (bf16_t)(pk2(a1, 0.f) & 0xffffu);
.LBB0_821:
	v_add_co_u32_e32 v18, vcc, 0x3000, v10
	s_nop 0
	s_nop 0
	v_addc_co_u32_e32 v19, vcc, 0, v11, vcc
	v_add_co_u32_e32 v38, vcc, 0x9000, v10
	s_nop 0
	s_nop 0
	v_addc_co_u32_e32 v39, vcc, 0, v11, vcc
	v_add_co_u32_e32 v40, vcc, 0xe000, v10
	s_mov_b64 s[24:25], vcc
	v_add_co_u32_e32 v42, vcc, 0x3000, v12
	s_nop 0
	s_nop 0
	v_addc_co_u32_e32 v43, vcc, 0, v13, vcc
	global_load_dword v42, v[42:43], off offset:3072
	s_nop 0
	global_load_dword v18, v[18:19], off offset:3072
	s_nop 0
	global_load_dword v19, v[38:39], off offset:1024
	v_addc_co_u32_e64 v41, vcc, 0, v11, s[24:25]
	global_load_dword v38, v[40:41], off offset:3072
	s_waitcnt vmcnt(6)
	v_fma_f32 v31, v31, v36, v33
	v_fmac_f32_e32 v33, v30, v36
	v_fmac_f32_e32 v31, v30, v35
	v_fmac_f32_e32 v33, v28, v35
	v_fmac_f32_e32 v31, v28, v37
	v_fmac_f32_e32 v33, v29, v37
	v_mul_f32_e32 v28, 0xbfb8aa3b, v31
	v_mul_f32_e32 v29, 0xbfb8aa3b, v33
	v_exp_f32_e32 v28, v28
	v_exp_f32_e32 v29, v29
	v_add_f32_e32 v28, 1.0, v28
	v_add_f32_e32 v29, 1.0, v29
	v_rcp_f32_e32 v28, v28
	v_rcp_f32_e32 v29, v29
	v_mul_f32_e32 v28, v31, v28
	v_mul_f32_e32 v29, v33, v29
	s_waitcnt vmcnt(2)
	v_fma_f32 v30, v34, v18, v42
	v_fmac_f32_e32 v42, v21, v18
	s_waitcnt vmcnt(1)
	v_fmac_f32_e32 v30, v21, v19
	v_fmac_f32_e32 v42, v32, v19
	s_waitcnt vmcnt(0)
	v_fmac_f32_e32 v30, v32, v38
	v_fmac_f32_e32 v42, v20, v38
	v_mul_f32_e32 v18, v28, v30
	v_mul_f32_e32 v19, v29, v42
	v_cvt_pk_bf16_f32 v18, v18, s0
	v_cvt_pk_bf16_f32 v19, v19, s0
	global_store_short v[16:17], v18, off offset:2048
	global_store_short v[14:15], v19, off offset:2048
	s_and_b64 exec, exec, s[16:17]
	s_cbranch_execz .LBB0_785
	v_add_u32_e32 v18, s37, v25
	v_ashrrev_i32_e32 v19, 31, v18
	v_lshlrev_b64 v[18:19], 12, v[18:19]
	v_lshl_add_u64 v[18:19], s[28:29], 0, v[18:19]
	v_lshl_add_u64 v[20:21], v[18:19], 0, v[0:1]
	global_load_dword v28, v[20:21], off
	global_load_dword v29, v[20:21], off offset:1024
	v_add_u32_e32 v18, s38, v25
	v_ashrrev_i32_e32 v19, 31, v18
	v_lshlrev_b64 v[18:19], 12, v[18:19]
	v_lshl_add_u64 v[18:19], s[28:29], 0, v[18:19]
	v_mov_b32_e32 v30, 0
	s_and_b64 vcc, exec, s[22:23]
	v_mov_b32_e32 v31, 0
	s_cbranch_vccnz .LBB0_824
	v_lshl_add_u64 v[32:33], v[18:19], 0, v[0:1]
	global_load_dword v31, v[32:33], off offset:2048

; __device__ __forceinline__ unsigned pk2(float lo, float hi) { f32x2_t v = {lo, hi}; bf16x2_t b = __builtin_convertvector(v, bf16x2_t); return __builtin_bit_cast(unsigned, b); }
; __device__ __forceinline__ float sigmoidf_(float v) { return fast_rcp(1.0f + fast_exp2(-v * LOG2E)); }
; __device__ __forceinline__ void fix_rows(bf16_t* A, const float* edge, const float* cw, const float* cb, int pm, int tid) {
;     ...
;     for (int it_ = 0; it_ < 6; ++it_) {
;         const int ch = tid + 512 * it_; if (ch >= DFF) break;
;         const int pn = ch >> 7, ci = ch & 127;
;         const float* E = edge + (size_t)(pm * 22 + pn) * 1024;
;         const float* P = hasprev ? edge + (size_t)((pm - 1) * 22 + pn) * 1024 : E;
;         float c0[2], c1[2];
; #pragma unroll
;         for (int gv = 0; gv < 2; ++gv) {
;             const int col = gv * 128 + ci, cc = gv * DFF + ch;
;             const float u0 = E[col], u1 = E[256 + col], p254 = hasprev ? P[512 + col] : 0.f, p255 = hasprev ? P[768 + col] : 0.f;
;             const float w0 = cw[cc], w1 = cw[UPN + cc], w2 = cw[2 * UPN + cc], bb = cb[cc];
;             c0[gv] = bb + w0 * p254 + w1 * p255 + w2 * u0; c1[gv] = bb + w0 * p255 + w1 * u0 + w2 * u1;
;         }
;         const float a0 = c0[0] * sigmoidf_(c0[0]) * c0[1], a1 = c1[0] * sigmoidf_(c1[0]) * c1[1];
;         A[(size_t)(pm * 256) * DFF + ch] = (bf16_t)(pk2(a0, 0.f) & 0xffffu);
;         A[(size_t)(pm * 256 + 1) * DFF + ch] = (bf16_t)(pk2(a1, 0.f) & 0xffffu);
.LBB0_830:
	v_add_co_u32_e32 v18, vcc, 0x4000, v10
	s_nop 0
	s_nop 0
	v_addc_co_u32_e32 v19, vcc, 0, v11, vcc
	v_add_co_u32_e32 v38, vcc, 0x9000, v10
	s_nop 0
	s_nop 0
	v_addc_co_u32_e32 v39, vcc, 0, v11, vcc
	v_add_co_u32_e32 v40, vcc, 0xf000, v10
	s_mov_b64 s[24:25], vcc
	v_add_co_u32_e32 v42, vcc, 0x4000, v12
	s_nop 0
	s_nop 0
	v_addc_co_u32_e32 v43, vcc, 0, v13, vcc
	global_load_dword v42, v[42:43], off offset:1024
	s_nop 0
	global_load_dword v18, v[18:19], off offset:1024
	s_nop 0
	global_load_dword v19, v[38:39], off offset:3072
	v_addc_co_u32_e64 v41, vcc, 0, v11, s[24:25]
	global_load_dword v38, v[40:41], off offset:1024
	s_waitcnt vmcnt(6)
	v_fma_f32 v31, v31, v36, v33
	v_fmac_f32_e32 v33, v30, v36
	v_fmac_f32_e32 v31, v30, v35
	v_fmac_f32_e32 v33, v28, v35
	v_fmac_f32_e32 v31, v28, v37
	v_fmac_f32_e32 v33, v29, v37
	v_mul_f32_e32 v28, 0xbfb8aa3b, v31
	v_mul_f32_e32 v29, 0xbfb8aa3b, v33
	v_exp_f32_e32 v28, v28
	v_exp_f32_e32 v29, v29
	v_add_f32_e32 v28, 1.0, v28
	v_add_f32_e32 v29, 1.0, v29
	v_rcp_f32_e32 v28, v28
	v_rcp_f32_e32 v29, v29
	v_mul_f32_e32 v28, v31, v28
	v_mul_f32_e32 v29, v33, v29
	s_waitcnt vmcnt(2)
	v_fma_f32 v30, v34, v18, v42
	v_fmac_f32_e32 v42, v21, v18
	s_waitcnt vmcnt(1)
	v_fmac_f32_e32 v30, v21, v19
	v_fmac_f32_e32 v42, v32, v19
	s_waitcnt vmcnt(0)
	v_fmac_f32_e32 v30, v32, v38
	v_fmac_f32_e32 v42, v20, v38
	v_mul_f32_e32 v18, v28, v30
	v_mul_f32_e32 v19, v29, v42
	v_cvt_pk_bf16_f32 v18, v18, s0
	v_cvt_pk_bf16_f32 v19, v19, s0
	global_store_short v[16:17], v18, off offset:3072
	global_store_short v[14:15], v19, off offset:3072
	s_and_b64 exec, exec, s[18:19]
	s_cbranch_execz .LBB0_785
	v_add_u32_e32 v18, s37, v26
	v_ashrrev_i32_e32 v19, 31, v18
	v_lshlrev_b64 v[18:19], 12, v[18:19]
	v_lshl_add_u64 v[18:19], s[28:29], 0, v[18:19]
	v_lshl_add_u64 v[20:21], v[18:19], 0, v[0:1]
	global_load_dword v28, v[20:21], off
	global_load_dword v29, v[20:21], off offset:1024
	v_add_u32_e32 v18, s38, v26
	v_ashrrev_i32_e32 v19, 31, v18
	v_lshlrev_b64 v[18:19], 12, v[18:19]
	v_lshl_add_u64 v[18:19], s[28:29], 0, v[18:19]
	v_mov_b32_e32 v32, 0
	s_and_b64 vcc, exec, s[22:23]
	v_mov_b32_e32 v33, 0
	s_cbranch_vccnz .LBB0_833
	v_lshl_add_u64 v[30:31], v[18:19], 0, v[0:1]
	global_load_dword v33, v[30:31], off offset:2048

; __device__ __forceinline__ unsigned pk2(float lo, float hi) { f32x2_t v = {lo, hi}; bf16x2_t b = __builtin_convertvector(v, bf16x2_t); return __builtin_bit_cast(unsigned, b); }
; __device__ __forceinline__ float sigmoidf_(float v) { return fast_rcp(1.0f + fast_exp2(-v * LOG2E)); }
; __device__ __forceinline__ void fix_rows(bf16_t* A, const float* edge, const float* cw, const float* cb, int pm, int tid) {
;     ...
;     for (int it_ = 0; it_ < 6; ++it_) {
;         const int ch = tid + 512 * it_; if (ch >= DFF) break;
;         const int pn = ch >> 7, ci = ch & 127;
;         const float* E = edge + (size_t)(pm * 22 + pn) * 1024;
;         const float* P = hasprev ? edge + (size_t)((pm - 1) * 22 + pn) * 1024 : E;
;         float c0[2], c1[2];
; #pragma unroll
;         for (int gv = 0; gv < 2; ++gv) {
;             const int col = gv * 128 + ci, cc = gv * DFF + ch;
;             const float u0 = E[col], u1 = E[256 + col], p254 = hasprev ? P[512 + col] : 0.f, p255 = hasprev ? P[768 + col] : 0.f;
;             const float w0 = cw[cc], w1 = cw[UPN + cc], w2 = cw[2 * UPN + cc], bb = cb[cc];
;             c0[gv] = bb + w0 * p254 + w1 * p255 + w2 * u0; c1[gv] = bb + w0 * p255 + w1 * u0 + w2 * u1;
;         }
;         const float a0 = c0[0] * sigmoidf_(c0[0]) * c0[1], a1 = c1[0] * sigmoidf_(c1[0]) * c1[1];
;         A[(size_t)(pm * 256) * DFF + ch] = (bf16_t)(pk2(a0, 0.f) & 0xffffu);
;         A[(size_t)(pm * 256 + 1) * DFF + ch] = (bf16_t)(pk2(a1, 0.f) & 0xffffu);
.LBB0_839:
	v_add_co_u32_e32 v18, vcc, 0x4000, v10
	s_nop 0
	s_nop 0
	v_addc_co_u32_e32 v19, vcc, 0, v11, vcc
	v_add_co_u32_e32 v38, vcc, 0xa000, v10
	s_nop 0
	s_nop 0
	v_addc_co_u32_e32 v39, vcc, 0, v11, vcc
	v_add_co_u32_e32 v40, vcc, 0xf000, v10
	s_mov_b64 s[24:25], vcc
	v_add_co_u32_e32 v42, vcc, 0x4000, v12
	s_nop 0
	s_nop 0
	v_addc_co_u32_e32 v43, vcc, 0, v13, vcc
	global_load_dword v42, v[42:43], off offset:3072
	s_nop 0
	global_load_dword v43, v[18:19], off offset:3072
	s_nop 0
	global_load_dword v38, v[38:39], off offset:1024
	v_addc_co_u32_e64 v41, vcc, 0, v11, s[24:25]
	global_load_dword v39, v[40:41], off offset:3072
	s_waitcnt vmcnt(6)
	v_fma_f32 v33, v33, v36, v31
	v_fmac_f32_e32 v31, v32, v36
	v_fmac_f32_e32 v31, v28, v35
	v_fmac_f32_e32 v31, v29, v37
	v_fmac_f32_e32 v33, v32, v35
	v_mul_f32_e32 v19, 0xbfb8aa3b, v31
	v_fmac_f32_e32 v33, v28, v37
	v_exp_f32_e32 v32, v19
	v_mul_f32_e32 v18, 0xbfb8aa3b, v33
	v_exp_f32_e32 v29, v18
	v_add_co_u32_e32 v18, vcc, 0x1000, v16
	v_add_f32_e32 v32, 1.0, v32
	v_rcp_f32_e32 v32, v32
	v_add_f32_e32 v29, 1.0, v29
	v_rcp_f32_e32 v35, v29
	v_addc_co_u32_e32 v19, vcc, 0, v17, vcc
	v_mul_f32_e32 v31, v31, v32
	v_mul_f32_e32 v33, v33, v35
	v_add_co_u32_e32 v28, vcc, 0x1000, v14
	s_waitcnt vmcnt(2)
	v_fma_f32 v32, v34, v43, v42
	v_fmac_f32_e32 v42, v21, v43
	s_waitcnt vmcnt(1)
	v_fmac_f32_e32 v32, v21, v38
	v_fmac_f32_e32 v42, v30, v38
	s_waitcnt vmcnt(0)
	v_fmac_f32_e32 v32, v30, v39
	v_fmac_f32_e32 v42, v20, v39
	v_mul_f32_e32 v20, v33, v32
	v_mul_f32_e32 v21, v31, v42
	v_cvt_pk_bf16_f32 v20, v20, s0
	v_addc_co_u32_e32 v29, vcc, 0, v15, vcc
	v_cvt_pk_bf16_f32 v21, v21, s0
	global_store_short v[18:19], v20, off
	global_store_short v[28:29], v21, off
	s_and_b64 exec, exec, s[20:21]
	s_cbranch_execz .LBB0_785
	v_add_u32_e32 v18, s37, v27
	v_ashrrev_i32_e32 v19, 31, v18
	v_lshlrev_b64 v[18:19], 12, v[18:19]
	v_lshl_add_u64 v[18:19], s[28:29], 0, v[18:19]
	v_lshl_add_u64 v[20:21], v[18:19], 0, v[0:1]
	global_load_dword v28, v[20:21], off
	global_load_dword v29, v[20:21], off offset:1024
	v_add_u32_e32 v18, s38, v27
	v_ashrrev_i32_e32 v19, 31, v18
	v_lshlrev_b64 v[18:19], 12, v[18:19]
	v_lshl_add_u64 v[18:19], s[28:29], 0, v[18:19]
	v_mov_b32_e32 v32, 0
	s_and_b64 vcc, exec, s[22:23]
	v_mov_b32_e32 v33, 0
	s_cbranch_vccnz .LBB0_842
	v_lshl_add_u64 v[30:31], v[18:19], 0, v[0:1]
	global_load_dword v33, v[30:31], off offset:2048

; __device__ __forceinline__ unsigned pk2(float lo, float hi) { f32x2_t v = {lo, hi}; bf16x2_t b = __builtin_convertvector(v, bf16x2_t); return __builtin_bit_cast(unsigned, b); }
; __device__ __forceinline__ float sigmoidf_(float v) { return fast_rcp(1.0f + fast_exp2(-v * LOG2E)); }
; __device__ __forceinline__ void fix_rows(bf16_t* A, const float* edge, const float* cw, const float* cb, int pm, int tid) {
;     ...
;     for (int it_ = 0; it_ < 6; ++it_) {
;         const int ch = tid + 512 * it_; if (ch >= DFF) break;
;         const int pn = ch >> 7, ci = ch & 127;
;         const float* E = edge + (size_t)(pm * 22 + pn) * 1024;
;         const float* P = hasprev ? edge + (size_t)((pm - 1) * 22 + pn) * 1024 : E;
;         float c0[2], c1[2];
; #pragma unroll
;         for (int gv = 0; gv < 2; ++gv) {
;             const int col = gv * 128 + ci, cc = gv * DFF + ch;
;             const float u0 = E[col], u1 = E[256 + col], p254 = hasprev ? P[512 + col] : 0.f, p255 = hasprev ? P[768 + col] : 0.f;
;             const float w0 = cw[cc], w1 = cw[UPN + cc], w2 = cw[2 * UPN + cc], bb = cb[cc];
;             c0[gv] = bb + w0 * p254 + w1 * p255 + w2 * u0; c1[gv] = bb + w0 * p255 + w1 * u0 + w2 * u1;
;         }
;         const float a0 = c0[0] * sigmoidf_(c0[0]) * c0[1], a1 = c1[0] * sigmoidf_(c1[0]) * c1[1];
;         A[(size_t)(pm * 256) * DFF + ch] = (bf16_t)(pk2(a0, 0.f) & 0xffffu);
;         A[(size_t)(pm * 256 + 1) * DFF + ch] = (bf16_t)(pk2(a1, 0.f) & 0xffffu);
.LBB0_1665:
	v_lshl_add_u64 v[10:11], v[14:15], 0, s[24:25]
	v_add_co_u32_e32 v14, vcc, s3, v10
	v_lshl_add_u64 v[12:13], v[16:17], 0, s[26:27]
	s_nop 0
	v_addc_co_u32_e32 v15, vcc, 0, v11, vcc
	v_add_co_u32_e32 v16, vcc, s33, v10
	s_nop 0
	s_nop 0
	v_addc_co_u32_e32 v17, vcc, 0, v11, vcc
	global_load_dword v36, v[14:15], off offset:3072
	global_load_dword v37, v[16:17], off offset:1024
	v_add_co_u32_e32 v14, vcc, s3, v12
	s_nop 0
	s_nop 0
	v_addc_co_u32_e32 v15, vcc, 0, v13, vcc
	global_load_dword v38, v[14:15], off offset:3072
	v_add_co_u32_e32 v14, vcc, s40, v10
	s_nop 0
	s_nop 0
	v_addc_co_u32_e32 v15, vcc, 0, v11, vcc
	global_load_dword v39, v[14:15], off offset:3072
	s_waitcnt vmcnt(6)
	v_fma_f32 v30, v30, v35, v29
	v_fmac_f32_e32 v29, v28, v35
	v_fmac_f32_e32 v30, v28, v33
	v_fmac_f32_e32 v29, v18, v33
	v_fmac_f32_e32 v30, v18, v34
	s_load_dwordx2 s[0:1], s[0:1], 0x98
	v_fmac_f32_e32 v29, v19, v34
	v_mul_f32_e32 v14, 0xbfb8aa3b, v30
	v_mul_f32_e32 v15, 0xbfb8aa3b, v29
	v_exp_f32_e32 v14, v14
	v_exp_f32_e32 v15, v15
	s_waitcnt lgkmcnt(0)
	s_add_u32 s21, s0, 0x9804000
	s_mul_i32 s20, s41, 0x160000
	v_add_f32_e32 v14, 1.0, v14
	s_addc_u32 s36, s1, 0
	s_lshl_b32 s37, s41, 8
	v_add_f32_e32 v15, 1.0, v15
	v_rcp_f32_e32 v18, v14
	s_mul_hi_i32 s1, s37, 0x1600
	s_add_u32 s0, s21, s20
	v_rcp_f32_e32 v19, v15
	s_addc_u32 s1, s36, s1
	s_or_b32 s20, s37, 1
	s_mul_hi_i32 s37, s20, 0x1600
	s_mulk_i32 s20, 0x1600
	v_lshl_add_u64 v[16:17], s[0:1], 0, v[8:9]
	s_add_u32 s0, s21, s20
	v_mul_f32_e32 v18, v30, v18
	s_addc_u32 s1, s36, s37
	v_mul_f32_e32 v19, v29, v19
	v_lshl_add_u64 v[14:15], s[0:1], 0, v[8:9]
	s_waitcnt vmcnt(1)
	v_fma_f32 v28, v32, v36, v38
	v_fmac_f32_e32 v38, v31, v36
	v_fmac_f32_e32 v28, v31, v37
	v_fmac_f32_e32 v38, v20, v37
	s_waitcnt vmcnt(0)
	v_fmac_f32_e32 v28, v20, v39
	v_fmac_f32_e32 v38, v21, v39
	v_mul_f32_e32 v18, v18, v28
	v_mul_f32_e32 v19, v19, v38
	v_cvt_pk_bf16_f32 v18, v18, s0
	v_cvt_pk_bf16_f32 v19, v19, s0
	global_store_short v[16:17], v18, off
	global_store_short v[14:15], v19, off
	s_and_b64 exec, exec, s[8:9]
	s_cbranch_execz .LBB0_1647
	v_add_u32_e32 v18, s42, v23
	v_ashrrev_i32_e32 v19, 31, v18
	v_lshlrev_b64 v[18:19], 12, v[18:19]
	v_lshl_add_u64 v[18:19], s[34:35], 0, v[18:19]
	v_lshl_add_u64 v[20:21], v[18:19], 0, v[0:1]
	global_load_dword v28, v[20:21], off
	global_load_dword v29, v[20:21], off offset:1024
	v_add_u32_e32 v18, s43, v23
	v_ashrrev_i32_e32 v19, 31, v18
	v_lshlrev_b64 v[18:19], 12, v[18:19]
	v_lshl_add_u64 v[18:19], s[34:35], 0, v[18:19]
	v_mov_b32_e32 v30, 0
	s_and_b64 vcc, exec, s[18:19]
	v_mov_b32_e32 v32, 0
	s_cbranch_vccnz .LBB0_1668
	v_lshl_add_u64 v[32:33], v[18:19], 0, v[0:1]
	global_load_dword v32, v[32:33], off offset:2048

; __device__ __forceinline__ unsigned pk2(float lo, float hi) { f32x2_t v = {lo, hi}; bf16x2_t b = __builtin_convertvector(v, bf16x2_t); return __builtin_bit_cast(unsigned, b); }
; __device__ __forceinline__ float sigmoidf_(float v) { return fast_rcp(1.0f + fast_exp2(-v * LOG2E)); }
; __device__ __forceinline__ void fix_rows(bf16_t* A, const float* edge, const float* cw, const float* cb, int pm, int tid) {
;     ...
;     for (int it_ = 0; it_ < 6; ++it_) {
;         const int ch = tid + 512 * it_; if (ch >= DFF) break;
;         const int pn = ch >> 7, ci = ch & 127;
;         const float* E = edge + (size_t)(pm * 22 + pn) * 1024;
;         const float* P = hasprev ? edge + (size_t)((pm - 1) * 22 + pn) * 1024 : E;
;         float c0[2], c1[2];
; #pragma unroll
;         for (int gv = 0; gv < 2; ++gv) {
;             const int col = gv * 128 + ci, cc = gv * DFF + ch;
;             const float u0 = E[col], u1 = E[256 + col], p254 = hasprev ? P[512 + col] : 0.f, p255 = hasprev ? P[768 + col] : 0.f;
;             const float w0 = cw[cc], w1 = cw[UPN + cc], w2 = cw[2 * UPN + cc], bb = cb[cc];
;             c0[gv] = bb + w0 * p254 + w1 * p255 + w2 * u0; c1[gv] = bb + w0 * p255 + w1 * u0 + w2 * u1;
;         }
;         const float a0 = c0[0] * sigmoidf_(c0[0]) * c0[1], a1 = c1[0] * sigmoidf_(c1[0]) * c1[1];
;         A[(size_t)(pm * 256) * DFF + ch] = (bf16_t)(pk2(a0, 0.f) & 0xffffu);
;         A[(size_t)(pm * 256 + 1) * DFF + ch] = (bf16_t)(pk2(a1, 0.f) & 0xffffu);
.LBB0_1674:
	v_add_co_u32_e32 v18, vcc, 0x3000, v10
	s_nop 0
	s_nop 0
	v_addc_co_u32_e32 v19, vcc, 0, v11, vcc
	v_add_co_u32_e32 v38, vcc, 0x8000, v10
	s_nop 0
	s_nop 0
	v_addc_co_u32_e32 v39, vcc, 0, v11, vcc
	v_add_co_u32_e32 v40, vcc, 0xe000, v10
	s_mov_b64 s[20:21], vcc
	v_add_co_u32_e32 v42, vcc, 0x3000, v12
	s_nop 0
	s_nop 0
	v_addc_co_u32_e32 v43, vcc, 0, v13, vcc
	global_load_dword v42, v[42:43], off offset:1024
	s_nop 0
	global_load_dword v18, v[18:19], off offset:1024
	s_nop 0
	global_load_dword v19, v[38:39], off offset:3072
	v_addc_co_u32_e64 v41, vcc, 0, v11, s[20:21]
	global_load_dword v38, v[40:41], off offset:1024
	s_waitcnt vmcnt(6)
	v_fma_f32 v32, v32, v35, v33
	v_fmac_f32_e32 v33, v30, v35
	v_fmac_f32_e32 v32, v30, v36
	v_fmac_f32_e32 v33, v28, v36
	v_fmac_f32_e32 v32, v28, v37
	v_fmac_f32_e32 v33, v29, v37
	v_mul_f32_e32 v28, 0xbfb8aa3b, v32
	v_mul_f32_e32 v29, 0xbfb8aa3b, v33
	v_exp_f32_e32 v28, v28
	v_exp_f32_e32 v29, v29
	v_add_f32_e32 v28, 1.0, v28
	v_add_f32_e32 v29, 1.0, v29
	v_rcp_f32_e32 v28, v28
	v_rcp_f32_e32 v29, v29
	v_mul_f32_e32 v28, v32, v28
	v_mul_f32_e32 v29, v33, v29
	s_waitcnt vmcnt(2)
	v_fma_f32 v30, v34, v18, v42
	v_fmac_f32_e32 v42, v21, v18
	s_waitcnt vmcnt(1)
	v_fmac_f32_e32 v30, v21, v19
	v_fmac_f32_e32 v42, v31, v19
	s_waitcnt vmcnt(0)
	v_fmac_f32_e32 v30, v31, v38
	v_fmac_f32_e32 v42, v20, v38
	v_mul_f32_e32 v18, v28, v30
	v_mul_f32_e32 v19, v29, v42
	v_cvt_pk_bf16_f32 v18, v18, s0
	v_cvt_pk_bf16_f32 v19, v19, s0
	global_store_short v[16:17], v18, off offset:1024
	global_store_short v[14:15], v19, off offset:1024
	s_and_b64 exec, exec, s[10:11]
	s_cbranch_execz .LBB0_1647
	v_add_u32_e32 v18, s42, v24
	v_ashrrev_i32_e32 v19, 31, v18
	v_lshlrev_b64 v[18:19], 12, v[18:19]
	v_lshl_add_u64 v[18:19], s[34:35], 0, v[18:19]
	v_lshl_add_u64 v[20:21], v[18:19], 0, v[0:1]
	global_load_dword v28, v[20:21], off
	global_load_dword v29, v[20:21], off offset:1024
	v_add_u32_e32 v18, s43, v24
	v_ashrrev_i32_e32 v19, 31, v18
	v_lshlrev_b64 v[18:19], 12, v[18:19]
	v_lshl_add_u64 v[18:19], s[34:35], 0, v[18:19]
	v_mov_b32_e32 v30, 0
	s_and_b64 vcc, exec, s[18:19]
	v_mov_b32_e32 v31, 0
	s_cbranch_vccnz .LBB0_1677
	v_lshl_add_u64 v[32:33], v[18:19], 0, v[0:1]
	global_load_dword v31, v[32:33], off offset:2048

; __device__ __forceinline__ unsigned pk2(float lo, float hi) { f32x2_t v = {lo, hi}; bf16x2_t b = __builtin_convertvector(v, bf16x2_t); return __builtin_bit_cast(unsigned, b); }
; __device__ __forceinline__ float sigmoidf_(float v) { return fast_rcp(1.0f + fast_exp2(-v * LOG2E)); }
; __device__ __forceinline__ void fix_rows(bf16_t* A, const float* edge, const float* cw, const float* cb, int pm, int tid) {
;     ...
;     for (int it_ = 0; it_ < 6; ++it_) {
;         const int ch = tid + 512 * it_; if (ch >= DFF) break;
;         const int pn = ch >> 7, ci = ch & 127;
;         const float* E = edge + (size_t)(pm * 22 + pn) * 1024;
;         const float* P = hasprev ? edge + (size_t)((pm - 1) * 22 + pn) * 1024 : E;
;         float c0[2], c1[2];
; #pragma unroll
;         for (int gv = 0; gv < 2; ++gv) {
;             const int col = gv * 128 + ci, cc = gv * DFF + ch;
;             const float u0 = E[col], u1 = E[256 + col], p254 = hasprev ? P[512 + col] : 0.f, p255 = hasprev ? P[768 + col] : 0.f;
;             const float w0 = cw[cc], w1 = cw[UPN + cc], w2 = cw[2 * UPN + cc], bb = cb[cc];
;             c0[gv] = bb + w0 * p254 + w1 * p255 + w2 * u0; c1[gv] = bb + w0 * p255 + w1 * u0 + w2 * u1;
;         }
;         const float a0 = c0[0] * sigmoidf_(c0[0]) * c0[1], a1 = c1[0] * sigmoidf_(c1[0]) * c1[1];
;         A[(size_t)(pm * 256) * DFF + ch] = (bf16_t)(pk2(a0, 0.f) & 0xffffu);
;         A[(size_t)(pm * 256 + 1) * DFF + ch] = (bf16_t)(pk2(a1, 0.f) & 0xffffu);
.LBB0_1683:
	v_add_co_u32_e32 v18, vcc, 0x3000, v10
	s_nop 0
	s_nop 0
	v_addc_co_u32_e32 v19, vcc, 0, v11, vcc
	v_add_co_u32_e32 v38, vcc, 0x9000, v10
	s_nop 0
	s_nop 0
	v_addc_co_u32_e32 v39, vcc, 0, v11, vcc
	v_add_co_u32_e32 v40, vcc, 0xe000, v10
	s_mov_b64 s[20:21], vcc
	v_add_co_u32_e32 v42, vcc, 0x3000, v12
	s_nop 0
	s_nop 0
	v_addc_co_u32_e32 v43, vcc, 0, v13, vcc
	global_load_dword v42, v[42:43], off offset:3072
	s_nop 0
	global_load_dword v18, v[18:19], off offset:3072
	s_nop 0
	global_load_dword v19, v[38:39], off offset:1024
	v_addc_co_u32_e64 v41, vcc, 0, v11, s[20:21]
	global_load_dword v38, v[40:41], off offset:3072
	s_waitcnt vmcnt(6)
	v_fma_f32 v31, v31, v36, v33
	v_fmac_f32_e32 v33, v30, v36
	v_fmac_f32_e32 v31, v30, v35
	v_fmac_f32_e32 v33, v28, v35
	v_fmac_f32_e32 v31, v28, v37
	v_fmac_f32_e32 v33, v29, v37
	v_mul_f32_e32 v28, 0xbfb8aa3b, v31
	v_mul_f32_e32 v29, 0xbfb8aa3b, v33
	v_exp_f32_e32 v28, v28
	v_exp_f32_e32 v29, v29
	v_add_f32_e32 v28, 1.0, v28
	v_add_f32_e32 v29, 1.0, v29
	v_rcp_f32_e32 v28, v28
	v_rcp_f32_e32 v29, v29
	v_mul_f32_e32 v28, v31, v28
	v_mul_f32_e32 v29, v33, v29
	s_waitcnt vmcnt(2)
	v_fma_f32 v30, v34, v18, v42
	v_fmac_f32_e32 v42, v21, v18
	s_waitcnt vmcnt(1)
	v_fmac_f32_e32 v30, v21, v19
	v_fmac_f32_e32 v42, v32, v19
	s_waitcnt vmcnt(0)
	v_fmac_f32_e32 v30, v32, v38
	v_fmac_f32_e32 v42, v20, v38
	v_mul_f32_e32 v18, v28, v30
	v_mul_f32_e32 v19, v29, v42
	v_cvt_pk_bf16_f32 v18, v18, s0
	v_cvt_pk_bf16_f32 v19, v19, s0
	global_store_short v[16:17], v18, off offset:2048
	global_store_short v[14:15], v19, off offset:2048
	s_and_b64 exec, exec, s[12:13]
	s_cbranch_execz .LBB0_1647
	v_add_u32_e32 v18, s42, v25
	v_ashrrev_i32_e32 v19, 31, v18
	v_lshlrev_b64 v[18:19], 12, v[18:19]
	v_lshl_add_u64 v[18:19], s[34:35], 0, v[18:19]
	v_lshl_add_u64 v[20:21], v[18:19], 0, v[0:1]
	global_load_dword v28, v[20:21], off
	global_load_dword v29, v[20:21], off offset:1024
	v_add_u32_e32 v18, s43, v25
	v_ashrrev_i32_e32 v19, 31, v18
	v_lshlrev_b64 v[18:19], 12, v[18:19]
	v_lshl_add_u64 v[18:19], s[34:35], 0, v[18:19]
	v_mov_b32_e32 v30, 0
	s_and_b64 vcc, exec, s[18:19]
	v_mov_b32_e32 v31, 0
	s_cbranch_vccnz .LBB0_1686
	v_lshl_add_u64 v[32:33], v[18:19], 0, v[0:1]
	global_load_dword v31, v[32:33], off offset:2048

; __device__ __forceinline__ unsigned pk2(float lo, float hi) { f32x2_t v = {lo, hi}; bf16x2_t b = __builtin_convertvector(v, bf16x2_t); return __builtin_bit_cast(unsigned, b); }
; __device__ __forceinline__ float sigmoidf_(float v) { return fast_rcp(1.0f + fast_exp2(-v * LOG2E)); }
; __device__ __forceinline__ void fix_rows(bf16_t* A, const float* edge, const float* cw, const float* cb, int pm, int tid) {
;     ...
;     for (int it_ = 0; it_ < 6; ++it_) {
;         const int ch = tid + 512 * it_; if (ch >= DFF) break;
;         const int pn = ch >> 7, ci = ch & 127;
;         const float* E = edge + (size_t)(pm * 22 + pn) * 1024;
;         const float* P = hasprev ? edge + (size_t)((pm - 1) * 22 + pn) * 1024 : E;
;         float c0[2], c1[2];
; #pragma unroll
;         for (int gv = 0; gv < 2; ++gv) {
;             const int col = gv * 128 + ci, cc = gv * DFF + ch;
;             const float u0 = E[col], u1 = E[256 + col], p254 = hasprev ? P[512 + col] : 0.f, p255 = hasprev ? P[768 + col] : 0.f;
;             const float w0 = cw[cc], w1 = cw[UPN + cc], w2 = cw[2 * UPN + cc], bb = cb[cc];
;             c0[gv] = bb + w0 * p254 + w1 * p255 + w2 * u0; c1[gv] = bb + w0 * p255 + w1 * u0 + w2 * u1;
;         }
;         const float a0 = c0[0] * sigmoidf_(c0[0]) * c0[1], a1 = c1[0] * sigmoidf_(c1[0]) * c1[1];
;         A[(size_t)(pm * 256) * DFF + ch] = (bf16_t)(pk2(a0, 0.f) & 0xffffu);
;         A[(size_t)(pm * 256 + 1) * DFF + ch] = (bf16_t)(pk2(a1, 0.f) & 0xffffu);
.LBB0_1692:
	v_add_co_u32_e32 v18, vcc, 0x4000, v10
	s_nop 0
	s_nop 0
	v_addc_co_u32_e32 v19, vcc, 0, v11, vcc
	v_add_co_u32_e32 v38, vcc, 0x9000, v10
	s_nop 0
	s_nop 0
	v_addc_co_u32_e32 v39, vcc, 0, v11, vcc
	v_add_co_u32_e32 v40, vcc, 0xf000, v10
	s_mov_b64 s[20:21], vcc
	v_add_co_u32_e32 v42, vcc, 0x4000, v12
	s_nop 0
	s_nop 0
	v_addc_co_u32_e32 v43, vcc, 0, v13, vcc
	global_load_dword v42, v[42:43], off offset:1024
	s_nop 0
	global_load_dword v18, v[18:19], off offset:1024
	s_nop 0
	global_load_dword v19, v[38:39], off offset:3072
	v_addc_co_u32_e64 v41, vcc, 0, v11, s[20:21]
	global_load_dword v38, v[40:41], off offset:1024
	s_waitcnt vmcnt(6)
	v_fma_f32 v31, v31, v36, v33
	v_fmac_f32_e32 v33, v30, v36
	v_fmac_f32_e32 v31, v30, v35
	v_fmac_f32_e32 v33, v28, v35
	v_fmac_f32_e32 v31, v28, v37
	v_fmac_f32_e32 v33, v29, v37
	v_mul_f32_e32 v28, 0xbfb8aa3b, v31
	v_mul_f32_e32 v29, 0xbfb8aa3b, v33
	v_exp_f32_e32 v28, v28
	v_exp_f32_e32 v29, v29
	v_add_f32_e32 v28, 1.0, v28
	v_add_f32_e32 v29, 1.0, v29
	v_rcp_f32_e32 v28, v28
	v_rcp_f32_e32 v29, v29
	v_mul_f32_e32 v28, v31, v28
	v_mul_f32_e32 v29, v33, v29
	s_waitcnt vmcnt(2)
	v_fma_f32 v30, v34, v18, v42
	v_fmac_f32_e32 v42, v21, v18
	s_waitcnt vmcnt(1)
	v_fmac_f32_e32 v30, v21, v19
	v_fmac_f32_e32 v42, v32, v19
	s_waitcnt vmcnt(0)
	v_fmac_f32_e32 v30, v32, v38
	v_fmac_f32_e32 v42, v20, v38
	v_mul_f32_e32 v18, v28, v30
	v_mul_f32_e32 v19, v29, v42
	v_cvt_pk_bf16_f32 v18, v18, s0
	v_cvt_pk_bf16_f32 v19, v19, s0
	global_store_short v[16:17], v18, off offset:3072
	global_store_short v[14:15], v19, off offset:3072
	s_and_b64 exec, exec, s[14:15]
	s_cbranch_execz .LBB0_1647
	v_add_u32_e32 v18, s42, v26
	v_ashrrev_i32_e32 v19, 31, v18
	v_lshlrev_b64 v[18:19], 12, v[18:19]
	v_lshl_add_u64 v[18:19], s[34:35], 0, v[18:19]
	v_lshl_add_u64 v[20:21], v[18:19], 0, v[0:1]
	global_load_dword v28, v[20:21], off
	global_load_dword v29, v[20:21], off offset:1024
	v_add_u32_e32 v18, s43, v26
	v_ashrrev_i32_e32 v19, 31, v18
	v_lshlrev_b64 v[18:19], 12, v[18:19]
	v_lshl_add_u64 v[18:19], s[34:35], 0, v[18:19]
	v_mov_b32_e32 v32, 0
	s_and_b64 vcc, exec, s[18:19]
	v_mov_b32_e32 v33, 0
	s_cbranch_vccnz .LBB0_1695
	v_lshl_add_u64 v[30:31], v[18:19], 0, v[0:1]
	global_load_dword v33, v[30:31], off offset:2048

; __device__ __forceinline__ unsigned pk2(float lo, float hi) { f32x2_t v = {lo, hi}; bf16x2_t b = __builtin_convertvector(v, bf16x2_t); return __builtin_bit_cast(unsigned, b); }
; __device__ __forceinline__ float sigmoidf_(float v) { return fast_rcp(1.0f + fast_exp2(-v * LOG2E)); }
; __device__ __forceinline__ void fix_rows(bf16_t* A, const float* edge, const float* cw, const float* cb, int pm, int tid) {
;     ...
;     for (int it_ = 0; it_ < 6; ++it_) {
;         const int ch = tid + 512 * it_; if (ch >= DFF) break;
;         const int pn = ch >> 7, ci = ch & 127;
;         const float* E = edge + (size_t)(pm * 22 + pn) * 1024;
;         const float* P = hasprev ? edge + (size_t)((pm - 1) * 22 + pn) * 1024 : E;
;         float c0[2], c1[2];
; #pragma unroll
;         for (int gv = 0; gv < 2; ++gv) {
;             const int col = gv * 128 + ci, cc = gv * DFF + ch;
;             const float u0 = E[col], u1 = E[256 + col], p254 = hasprev ? P[512 + col] : 0.f, p255 = hasprev ? P[768 + col] : 0.f;
;             const float w0 = cw[cc], w1 = cw[UPN + cc], w2 = cw[2 * UPN + cc], bb = cb[cc];
;             c0[gv] = bb + w0 * p254 + w1 * p255 + w2 * u0; c1[gv] = bb + w0 * p255 + w1 * u0 + w2 * u1;
;         }
;         const float a0 = c0[0] * sigmoidf_(c0[0]) * c0[1], a1 = c1[0] * sigmoidf_(c1[0]) * c1[1];
;         A[(size_t)(pm * 256) * DFF + ch] = (bf16_t)(pk2(a0, 0.f) & 0xffffu);
;         A[(size_t)(pm * 256 + 1) * DFF + ch] = (bf16_t)(pk2(a1, 0.f) & 0xffffu);
.LBB0_1701:
	v_add_co_u32_e32 v18, vcc, 0x4000, v10
	s_nop 0
	s_nop 0
	v_addc_co_u32_e32 v19, vcc, 0, v11, vcc
	v_add_co_u32_e32 v38, vcc, 0xa000, v10
	s_nop 0
	s_nop 0
	v_addc_co_u32_e32 v39, vcc, 0, v11, vcc
	v_add_co_u32_e32 v40, vcc, 0xf000, v10
	s_mov_b64 s[20:21], vcc
	v_add_co_u32_e32 v42, vcc, 0x4000, v12
	s_nop 0
	s_nop 0
	v_addc_co_u32_e32 v43, vcc, 0, v13, vcc
	global_load_dword v42, v[42:43], off offset:3072
	s_nop 0
	global_load_dword v43, v[18:19], off offset:3072
	s_nop 0
	global_load_dword v38, v[38:39], off offset:1024
	v_addc_co_u32_e64 v41, vcc, 0, v11, s[20:21]
	global_load_dword v39, v[40:41], off offset:3072
	s_waitcnt vmcnt(6)
	v_fma_f32 v33, v33, v36, v31
	v_fmac_f32_e32 v31, v32, v36
	v_fmac_f32_e32 v31, v28, v35
	v_fmac_f32_e32 v31, v29, v37
	v_fmac_f32_e32 v33, v32, v35
	v_mul_f32_e32 v19, 0xbfb8aa3b, v31
	v_fmac_f32_e32 v33, v28, v37
	v_exp_f32_e32 v32, v19
	v_mul_f32_e32 v18, 0xbfb8aa3b, v33
	v_exp_f32_e32 v29, v18
	v_add_co_u32_e32 v18, vcc, 0x1000, v16
	v_add_f32_e32 v32, 1.0, v32
	v_rcp_f32_e32 v32, v32
	v_add_f32_e32 v29, 1.0, v29
	v_rcp_f32_e32 v35, v29
	v_addc_co_u32_e32 v19, vcc, 0, v17, vcc
	v_mul_f32_e32 v31, v31, v32
	v_mul_f32_e32 v33, v33, v35
	v_add_co_u32_e32 v28, vcc, 0x1000, v14
	s_waitcnt vmcnt(2)
	v_fma_f32 v32, v34, v43, v42
	v_fmac_f32_e32 v42, v21, v43
	s_waitcnt vmcnt(1)
	v_fmac_f32_e32 v32, v21, v38
	v_fmac_f32_e32 v42, v30, v38
	s_waitcnt vmcnt(0)
	v_fmac_f32_e32 v32, v30, v39
	v_fmac_f32_e32 v42, v20, v39
	v_mul_f32_e32 v20, v33, v32
	v_mul_f32_e32 v21, v31, v42
	v_cvt_pk_bf16_f32 v20, v20, s0
	v_addc_co_u32_e32 v29, vcc, 0, v15, vcc
	v_cvt_pk_bf16_f32 v21, v21, s0
	global_store_short v[18:19], v20, off
	global_store_short v[28:29], v21, off
	s_and_b64 exec, exec, s[16:17]
	s_cbranch_execz .LBB0_1647
	v_add_u32_e32 v18, s42, v27
	v_ashrrev_i32_e32 v19, 31, v18
	v_lshlrev_b64 v[18:19], 12, v[18:19]
	v_lshl_add_u64 v[18:19], s[34:35], 0, v[18:19]
	v_lshl_add_u64 v[20:21], v[18:19], 0, v[0:1]
	global_load_dword v28, v[20:21], off
	global_load_dword v29, v[20:21], off offset:1024
	v_add_u32_e32 v18, s43, v27
	v_ashrrev_i32_e32 v19, 31, v18
	v_lshlrev_b64 v[18:19], 12, v[18:19]
	v_lshl_add_u64 v[18:19], s[34:35], 0, v[18:19]
	v_mov_b32_e32 v32, 0
	s_and_b64 vcc, exec, s[18:19]
	v_mov_b32_e32 v33, 0
	s_cbranch_vccnz .LBB0_1704
	v_lshl_add_u64 v[30:31], v[18:19], 0, v[0:1]
	global_load_dword v33, v[30:31], off offset:2048
